# baseline (speedup 1.0000x reference)
.LBB0_71:
	v_cmp_gt_u32_e64 s[2:3], s21, v12
	v_mov_b32_e32 v14, 0
	s_and_saveexec_b64 s[14:15], s[2:3]
	s_cbranch_execz .LBB0_73
	v_lshlrev_b32_e32 v2, 9, v12
	v_lshl_add_u64 v[14:15], v[8:9], 0, v[2:3]
	global_load_dword v14, v[14:15], off offset:512

.LBB0_75:
	v_cmp_gt_u32_e64 s[2:3], s21, v12
	v_mov_b32_e32 v15, 0
	s_and_saveexec_b64 s[14:15], s[2:3]
	s_cbranch_execz .LBB0_77
	v_lshlrev_b32_e32 v2, 9, v12
	v_lshl_add_u64 v[16:17], v[8:9], 0, v[2:3]
	global_load_dword v15, v[16:17], off offset:1024

.LBB0_79:
	v_cmp_gt_u32_e64 s[2:3], s21, v12
	v_mov_b32_e32 v16, 0
	s_and_saveexec_b64 s[14:15], s[2:3]
	s_cbranch_execz .LBB0_81
	v_lshlrev_b32_e32 v2, 9, v12
	v_lshl_add_u64 v[16:17], v[8:9], 0, v[2:3]
	global_load_dword v16, v[16:17], off offset:1536

.LBB0_83:
	v_cmp_gt_u32_e64 s[2:3], s21, v12
	v_mov_b32_e32 v17, 0
	s_and_saveexec_b64 s[14:15], s[2:3]
	s_cbranch_execz .LBB0_85
	v_lshlrev_b32_e32 v2, 9, v12
	v_lshl_add_u64 v[18:19], v[8:9], 0, v[2:3]
	global_load_dword v17, v[18:19], off offset:2048

.LBB0_87:
	v_cmp_gt_u32_e64 s[2:3], s21, v12
	v_mov_b32_e32 v18, 0
	s_and_saveexec_b64 s[14:15], s[2:3]
	s_cbranch_execz .LBB0_89
	v_lshlrev_b32_e32 v2, 9, v12
	v_lshl_add_u64 v[18:19], v[8:9], 0, v[2:3]
	global_load_dword v18, v[18:19], off offset:2560

.LBB0_91:
	v_cmp_gt_u32_e64 s[2:3], s21, v12
	v_mov_b32_e32 v19, 0
	s_and_saveexec_b64 s[14:15], s[2:3]
	s_cbranch_execz .LBB0_93
	v_lshlrev_b32_e32 v2, 9, v12
	v_lshl_add_u64 v[20:21], v[8:9], 0, v[2:3]
	global_load_dword v19, v[20:21], off offset:3072

.LBB0_95:
	v_cmp_gt_u32_e32 vcc, s21, v12
	v_mov_b32_e32 v2, 0
	s_and_saveexec_b64 s[12:13], vcc
	s_cbranch_execz .LBB0_32
	v_lshlrev_b32_e32 v2, 9, v12
	v_lshl_add_u64 v[6:7], v[8:9], 0, v[2:3]
	global_load_dword v2, v[6:7], off offset:3584
	s_branch .LBB0_32

.LBB0_137:
	v_cmp_gt_u32_e32 vcc, s21, v10
	v_mov_b32_e32 v12, 0
	s_and_saveexec_b64 s[14:15], vcc
	s_cbranch_execz .LBB0_139
	v_lshlrev_b32_e32 v2, 14, v10
	v_lshl_add_u64 v[12:13], v[8:9], 0, v[2:3]
	v_add_co_u32_e32 v12, vcc, 0x4000, v12
	s_nop 1
	v_addc_co_u32_e32 v13, vcc, 0, v13, vcc
	global_load_dword v12, v[12:13], off

.LBB0_141:
	v_cmp_gt_u32_e32 vcc, s21, v10
	v_mov_b32_e32 v13, 0
	s_and_saveexec_b64 s[14:15], vcc
	s_cbranch_execz .LBB0_143
	v_lshlrev_b32_e32 v2, 14, v10
	v_lshl_add_u64 v[14:15], v[8:9], 0, v[2:3]
	v_add_co_u32_e32 v14, vcc, 0x8000, v14
	s_nop 1
	v_addc_co_u32_e32 v15, vcc, 0, v15, vcc
	global_load_dword v13, v[14:15], off

.LBB0_145:
	v_cmp_gt_u32_e32 vcc, s21, v10
	v_mov_b32_e32 v14, 0
	s_and_saveexec_b64 s[14:15], vcc
	s_cbranch_execz .LBB0_147
	v_lshlrev_b32_e32 v2, 14, v10
	v_lshl_add_u64 v[14:15], v[8:9], 0, v[2:3]
	v_add_co_u32_e32 v14, vcc, 0xc000, v14
	s_nop 1
	v_addc_co_u32_e32 v15, vcc, 0, v15, vcc
	global_load_dword v14, v[14:15], off

.LBB0_149:
	v_cmp_gt_u32_e32 vcc, s21, v10
	v_mov_b32_e32 v15, 0
	s_and_saveexec_b64 s[14:15], vcc
	s_cbranch_execz .LBB0_151
	v_lshlrev_b32_e32 v2, 14, v10
	v_lshl_add_u64 v[16:17], v[8:9], 0, v[2:3]
	v_add_co_u32_e32 v16, vcc, 0x10000, v16
	s_nop 1
	v_addc_co_u32_e32 v17, vcc, 0, v17, vcc
	global_load_dword v15, v[16:17], off

.LBB0_153:
	v_cmp_gt_u32_e32 vcc, s21, v10
	v_mov_b32_e32 v16, 0
	s_and_saveexec_b64 s[14:15], vcc
	s_cbranch_execz .LBB0_155
	v_lshlrev_b32_e32 v2, 14, v10
	v_lshl_add_u64 v[16:17], v[8:9], 0, v[2:3]
	v_add_co_u32_e32 v16, vcc, 0x14000, v16
	s_nop 1
	v_addc_co_u32_e32 v17, vcc, 0, v17, vcc
	global_load_dword v16, v[16:17], off

.LBB0_157:
	v_cmp_gt_u32_e32 vcc, s21, v10
	v_mov_b32_e32 v17, 0
	s_and_saveexec_b64 s[14:15], vcc
	s_cbranch_execz .LBB0_159
	v_lshlrev_b32_e32 v2, 14, v10
	v_lshl_add_u64 v[18:19], v[8:9], 0, v[2:3]
	v_add_co_u32_e32 v18, vcc, 0x18000, v18
	s_nop 1
	v_addc_co_u32_e32 v19, vcc, 0, v19, vcc
	global_load_dword v17, v[18:19], off

.LBB0_161:
	v_cmp_gt_u32_e32 vcc, s21, v10
	v_mov_b32_e32 v2, 0
	s_and_saveexec_b64 s[12:13], vcc
	s_cbranch_execz .LBB0_98
	v_lshlrev_b32_e32 v2, 14, v10
	v_lshl_add_u64 v[6:7], v[8:9], 0, v[2:3]
	v_add_co_u32_e32 v6, vcc, 0x1c000, v6
	s_nop 1
	v_addc_co_u32_e32 v7, vcc, 0, v7, vcc
	global_load_dword v2, v[6:7], off
	s_branch .LBB0_98
